# scan phase: queue-A workgroups that own a 7th gates-GEMM tile do not take a second queue-A job
# speedup vs baseline: 1.0026x; 1.0026x over previous
.LBB0_421:
	s_or_b64 exec, exec, s[0:1]
	s_mov_b32 s98, 0
	v_writelane_b32 v250, s98, 42
	v_readlane_b32 s6, v252, 0
	v_readlane_b32 s7, v252, 1
	s_mov_b64 s[0:1], s[6:7]
	v_readlane_b32 s8, v250, 5
	s_waitcnt lgkmcnt(0)
	s_barrier
	v_readlane_b32 s9, v250, 6
	s_load_dwordx2 s[0:1], s[0:1], 0x158
	s_and_b64 s[4:5], s[8:9], exec
	s_mov_b64 s[4:5], s[6:7]
	s_load_dwordx2 s[4:5], s[4:5], 0x158
	s_cselect_b32 s6, 64, 0
	v_writelane_b32 v250, s6, 12
	s_lshl_b32 s6, s6, 2
	s_waitcnt lgkmcnt(0)
	s_add_u32 s0, s0, s6
	s_addc_u32 s1, s1, 0
	v_writelane_b32 v250, s0, 13
	v_mov_b32_e32 v0, v162
	s_mov_b32 s71, s73
	v_writelane_b32 v250, s1, 14
	s_add_u32 s0, s4, s6
	s_addc_u32 s1, s5, 0
	v_writelane_b32 v250, s0, 15
	v_sub_u32_e32 v0, 0, v0
	v_readlane_b32 s24, v252, 28
	v_writelane_b32 v250, s1, 16
	v_readlane_b32 s0, v251, 21
	v_readlane_b32 s1, v251, 22
	s_nop 0
	v_cmp_eq_u32_e64 s[0:1], s0, v0
	s_nop 1
	v_writelane_b32 v250, s0, 10
	s_nop 1
	v_writelane_b32 v250, s1, 11
	s_and_b64 s[0:1], s[8:9], exec
	s_cselect_b32 s0, 0x4000, 0
	v_writelane_b32 v250, s0, 5
	s_cselect_b32 s0, 8, 0
	v_writelane_b32 v250, s0, 17
	s_cselect_b32 s0, 0x800, 0
	v_writelane_b32 v250, s0, 18
	s_cselect_b32 s0, 0x80, 0
	s_mov_b32 s1, s73
	v_writelane_b32 v250, s0, 19
	s_nop 1
	v_writelane_b32 v250, s1, 20
	s_cselect_b32 s0, 0x400, 0
	v_writelane_b32 v250, s0, 21
	s_cselect_b32 s0, 0x200000, 0
	v_writelane_b32 v250, s0, 22
	s_cselect_b32 s0, 0x200, 0
	v_writelane_b32 v250, s0, 23
	v_writelane_b32 v250, s70, 8
	s_nop 1
	v_writelane_b32 v250, s71, 9
	s_branch .LBB0_425

.LBB0_447:
	s_barrier
	s_mov_b64 s[0:1], exec
	v_readlane_b32 s4, v250, 10
	v_readlane_b32 s5, v250, 11
	s_and_b64 s[4:5], s[0:1], s[4:5]
	s_mov_b64 exec, s[4:5]
	s_cbranch_execz .LBB0_451
	s_mov_b64 s[6:7], exec
	v_mbcnt_lo_u32_b32 v0, s6, 0
	v_mbcnt_hi_u32_b32 v0, s7, v0
	v_cmp_eq_u32_e32 vcc, 0, v0
	s_and_saveexec_b64 s[4:5], vcc
	s_cbranch_execz .LBB0_450
	s_bcnt1_i32_b64 s6, s[6:7]
	v_mov_b32_e32 v2, s6
	v_readlane_b32 s98, v250, 42
	s_nop 3
	s_add_u32 s99, s98, 1
	s_nop 0
	v_writelane_b32 v250, s99, 42
	s_cmp_eq_u32 s98, 0
	s_cbranch_scc1 .Lqa_pop
	s_cmp_lg_u32 s24, 1
	s_cbranch_scc1 .Lqa_pop
	v_readlane_b32 s98, v251, 34
	s_nop 3
	s_sub_u32 s98, s98, 0x80
	s_cmp_lt_u32 s98, 24
	s_cbranch_scc0 .Lqa_pop
	v_mov_b32_e32 v2, 0xc0
	s_branch .LBB0_450
.Lqa_pop:
	v_readlane_b32 s6, v250, 13
	v_readlane_b32 s7, v250, 14
	s_nop 4
	global_atomic_add v2, v1, v2, s[6:7] sc0
